# v17 + seq loader waves prefetch step n+3 operands into L2 (dword touches), counted vmcnt(2) at step end
# baseline (speedup 1.0000x reference)
; DI int otid() { int t = threadIdx.x; asm volatile("" : "+v"(t)); return t; }
; #define LAS __attribute__((address_space(3)))
; #define DMA_GT(cid_, slot_) do { if (wave == 0) __builtin_amdgcn_global_load_lds((const unsigned*)(GGC + ((size_t)(cid_) * 8 + hv) * 256 + lane * 4), \
;       (LAS unsigned*)((LAS char*)lds_all + 131072 + (slot_) * 1024 + lane * 16), 16, 0, 0); } while (0)
; DI void phase_gdn_seq(const Params& p, const Sub& s, char* lds_all) {
;     ...
;   for (int rb = blockIdx.x; rb < 256; rb += gridDim.x) {
;     if ((rb >= 128) != s.samp) continue;
;     const int hh = otid() >> 8;
;     const bool act = rb >= 128 || hh == 0;
;     const int it = rb < 128 ? rb : 128 + (rb - 128) * 2 + hh;
;     const bool samp = it >= 128;
;     int b, hv, half, nsteps, cid0;
;     if (!samp) { b = it >> 4; hv = (it >> 1) & 7; half = it & 1; nsteps = 128; cid0 = b * 128; }
;     else { const int s = it - 128; b = s >> 4; hv = (s >> 1) & 7; half = s & 1; nsteps = 1; cid0 = 1024 + b; }
;     const int hq = hv >> 1, dv0 = half * 64 + wave * 16;
;     const int tv = samp ? 16 : 64;
;     f32x4 S[8];
; #pragma unroll
;     for (int m = 0; m < 8; ++m) {
;       S[m] = (f32x4){0.f, 0.f, 0.f, 0.f};
;       if (samp && act) {
; #pragma unroll
;         for (int j = 0; j < 4; ++j) S[m][j] = p.st_gdn[(((size_t)b * 8 + hv) * 128 + m * 16 + 4 * fq + j) * 128 + dv0 + fr];
;       }
;     }
;     ...
;     char* lbase = rb < 128 ? lds_all : lds_all + ((otid() >> 8) << 16);
;     LAS char* l3 = (LAS char*)lbase;
;     ...
;     const bool ldr = rb < 128 ? (hh == 1) : true;
;     if (ldr) { DMA_WU(cid0, 0); DMA_QK(cid0, 0); DMA_GT(cid0, rb < 128 ? 0 : hh); }
.LBB0_1959:
	s_cmpk_gt_i32 s62, 0x7f
	s_cbranch_scc1 .LBB0_1958
	s_and_b32 s98, s62, 7
	s_lshl_b32 s98, s98, 4
	s_lshr_b32 s99, s62, 3
	s_or_b32 s98, s98, s99
	s_ashr_i32 s38, s98, 4
	v_mov_b32_e32 v0, v182
	s_lshl_b32 s0, s38, 7
	s_lshr_b32 s1, s98, 1
	v_and_b32_e32 v2, 0xffffff00, v0
	s_bfe_u32 s12, s98, 0x30001
	s_and_b32 s39, s98, 1
	s_mov_b32 s100, s39
	s_bfe_u32 s40, s1, 0x20001
	v_cmp_eq_u32_e64 s[6:7], s53, v2
	v_cmp_ne_u32_e32 vcc, s53, v2
	s_and_saveexec_b64 s[2:3], vcc
	s_xor_b64 s[2:3], exec, s[2:3]
	s_lshl_b32 s4, s39, 12
	s_mov_b32 s5, s13
	s_lshl_b32 s8, s40, 13
	s_mov_b32 s9, s13
	s_ashr_i32 s1, s0, 31
	s_or_saveexec_b64 s[2:3], s[2:3]
	v_mov_b64_e32 v[2:3], s[0:1]
	v_mov_b64_e32 v[6:7], s[8:9]
	v_mov_b64_e32 v[4:5], s[4:5]
	v_mov_b64_e32 v[8:9], s[12:13]
	s_xor_b64 exec, exec, s[2:3]
	s_cbranch_execz .LBB0_1966
	s_ashr_i32 s1, s0, 31
	s_lshl_b64 s[4:5], s[0:1], 3
	s_or_b32 s4, s4, s12
	s_lshl_b64 s[8:9], s[4:5], 13
	s_lshl_b64 s[64:65], s[4:5], 14
	s_add_u32 s66, s33, s64
	s_addc_u32 s67, s42, s65
	v_mov_b32_e32 v73, v1
	v_lshl_add_u64 v[2:3], s[66:67], 0, v[72:73]
	v_mov_b32_e32 v75, v1
	v_readfirstlane_b32 s41, v106
	v_lshl_add_u64 v[2:3], v[2:3], 0, v[74:75]
	s_mov_b32 m0, s41
	v_mov_b32_e32 v77, v1
	global_load_lds_dwordx4 v[2:3], off
	v_lshl_add_u64 v[2:3], s[66:67], 0, v[76:77]
	v_readfirstlane_b32 s41, v107
	v_lshl_add_u64 v[2:3], v[2:3], 0, v[74:75]
	s_mov_b32 m0, s41
	v_mov_b32_e32 v79, v1
	global_load_lds_dwordx4 v[2:3], off
	v_lshl_add_u64 v[2:3], s[66:67], 0, v[78:79]
	v_readfirstlane_b32 s41, v108
	v_lshl_add_u64 v[2:3], v[2:3], 0, v[74:75]
	s_mov_b32 m0, s41
	v_readfirstlane_b32 s41, v109
	global_load_lds_dwordx4 v[2:3], off
	v_mov_b32_e32 v81, v1
	s_mov_b32 m0, s41
	s_add_u32 s41, s43, s64
	v_lshl_add_u64 v[2:3], s[66:67], 0, v[80:81]
	s_addc_u32 s63, s44, s65
	s_lshl_b32 s64, s39, 13
	v_lshl_add_u64 v[2:3], v[2:3], 0, v[74:75]
	s_add_u32 s64, s41, s64
	v_readfirstlane_b32 s41, v112
	global_load_lds_dwordx4 v[2:3], off
	s_addc_u32 s65, s63, 0
	s_mov_b32 m0, s41
	v_readfirstlane_b32 s41, v114
	global_load_lds_dwordx4 v111, s[64:65]
	s_mov_b32 m0, s41
	s_lshl_b32 s41, s40, 14
	global_load_lds_dwordx4 v113, s[64:65]
	s_lshl_b64 s[64:65], s[0:1], 16
	s_or_b32 s41, s64, s41
	s_add_u32 s66, s47, s41
	s_addc_u32 s67, s48, s65
	s_add_u32 s64, s49, s41
	v_lshl_add_u64 v[2:3], s[66:67], 0, v[72:73]
	v_readfirstlane_b32 s41, v115
	v_lshl_add_u64 v[2:3], v[2:3], 0, v[74:75]
	s_mov_b32 m0, s41
	v_readfirstlane_b32 s41, v116
	global_load_lds_dwordx4 v[2:3], off
	v_lshl_add_u64 v[2:3], s[66:67], 0, v[76:77]
	v_lshl_add_u64 v[2:3], v[2:3], 0, v[74:75]
	s_mov_b32 m0, s41
	v_readfirstlane_b32 s41, v117
	global_load_lds_dwordx4 v[2:3], off
	v_lshl_add_u64 v[2:3], s[66:67], 0, v[78:79]
	v_lshl_add_u64 v[2:3], v[2:3], 0, v[74:75]
	s_mov_b32 m0, s41
	v_readfirstlane_b32 s41, v118
	global_load_lds_dwordx4 v[2:3], off
	v_lshl_add_u64 v[2:3], s[66:67], 0, v[80:81]
	s_addc_u32 s65, s50, s65
	v_lshl_add_u64 v[2:3], v[2:3], 0, v[74:75]
	s_mov_b32 m0, s41
	v_mov_b32_e32 v83, v1
	global_load_lds_dwordx4 v[2:3], off
	v_lshl_add_u64 v[2:3], s[64:65], 0, v[82:83]
	v_mov_b32_e32 v85, v1
	v_readfirstlane_b32 s41, v119
	v_lshl_add_u64 v[2:3], v[2:3], 0, v[84:85]
	s_mov_b32 m0, s41
	v_mov_b32_e32 v87, v1
	global_load_lds_dwordx4 v[2:3], off
	v_lshl_add_u64 v[2:3], s[64:65], 0, v[86:87]
	v_mov_b32_e32 v89, v1
	v_readfirstlane_b32 s41, v120
	v_lshl_add_u64 v[2:3], v[2:3], 0, v[88:89]
	s_mov_b32 m0, s41
	v_mov_b32_e32 v91, v1
	global_load_lds_dwordx4 v[2:3], off
	v_lshl_add_u64 v[2:3], s[64:65], 0, v[90:91]
	v_mov_b32_e32 v93, v1
	v_readfirstlane_b32 s41, v121
	v_lshl_add_u64 v[2:3], v[2:3], 0, v[92:93]
	s_mov_b32 m0, s41
	v_mov_b32_e32 v95, v1
	global_load_lds_dwordx4 v[2:3], off
	v_lshl_add_u64 v[2:3], s[64:65], 0, v[94:95]
	v_mov_b32_e32 v97, v1
	v_readfirstlane_b32 s41, v122
	s_add_u32 s8, s45, s8
	v_lshl_add_u64 v[2:3], v[2:3], 0, v[96:97]
	s_mov_b32 m0, s41
	s_addc_u32 s9, s46, s9
	global_load_lds_dwordx4 v[2:3], off
	v_lshl_add_u64 v[2:3], s[8:9], 0, v[82:83]
	v_readfirstlane_b32 s41, v123
	v_lshl_add_u64 v[2:3], v[2:3], 0, v[84:85]
	s_mov_b32 m0, s41
	s_nop 0
	global_load_lds_dwordx4 v[2:3], off
	v_lshl_add_u64 v[2:3], s[8:9], 0, v[86:87]
	v_readfirstlane_b32 s8, v124
	v_lshl_add_u64 v[2:3], v[2:3], 0, v[88:89]
	s_mov_b32 m0, s8
	s_nop 0
	global_load_lds_dwordx4 v[2:3], off
	s_and_saveexec_b64 s[8:9], s[14:15]
	s_cbranch_execz .LBB0_1965
	s_lshl_b64 s[4:5], s[4:5], 10
	v_lshl_add_u64 v[2:3], v[70:71], 0, s[4:5]
	v_readfirstlane_b32 s4, v125
	s_mov_b32 m0, s4
	s_nop 0
	global_load_lds_dwordx4 v[2:3], off

; DI void phase_gdn_seq(const Params& p, const Sub& s, char* lds_all) {
;     ...
;       asm volatile("s_waitcnt vmcnt(0)" ::: "memory");
;       __syncthreads();
.LBB0_1967:
	s_or_b64 exec, exec, s[0:1]
	s_cmp_eq_u64 s[6:7], 0
	s_cbranch_scc1 .Lseq_cw
	s_waitcnt vmcnt(2)
	s_branch .Lseq_wd

; #define DMA_GT(cid_, slot_) do { if (wave == 0) __builtin_amdgcn_global_load_lds((const unsigned*)(GGC + ((size_t)(cid_) * 8 + hv) * 256 + lane * 4), \
;       (LAS unsigned*)((LAS char*)lds_all + 131072 + (slot_) * 1024 + lane * 16), 16, 0, 0); } while (0)
; DI void phase_gdn_seq(const Params& p, const Sub& s, char* lds_all) {
;     ...
;     for (int n = 0; n < nsteps; ++n) {
;       const int tid = VTID, lane = tid & 63, wave = tid >> 6, fr = lane & 15, fq = lane >> 4;
;       const int dv0 = half * 64 + wave * 16;
;       const int row0 = samp ? MP + b * 16 : (cid0 + n) * 64;
;       const int bcur = (rb < 128) ? ((n & 1) << 16) : 0, bnxt = bcur ^ 65536;
;       const char* Lw = lbase + bcur; const char* Lq = Lw + 16384; const char* Lk = Lw + 32768; const char* Lqk = Lw + 49152; const char* Lu = Lw + 57344;
;       if (n + 1 < nsteps) {
;         if (ldr) { DMA_WU(cid0 + n + 1, bnxt); DMA_QK(cid0 + n + 1, bnxt); DMA_GT(cid0 + n + 1, (n + 1) & 1); }
;       }
;     ...
;       asm volatile("s_waitcnt vmcnt(0)" ::: "memory");
;       __syncthreads();
.Lseq_wd:
	s_addk_i32 s4, 0x400
	s_add_i32 s5, s5, 64
	s_add_i32 s39, s39, 1
	v_lshl_add_u64 v[58:59], v[58:59], 0, s[30:31]
	v_lshl_add_u64 v[60:61], v[60:61], 0, s[34:35]
	v_lshl_add_u64 v[62:63], v[62:63], 0, s[34:35]
	v_lshl_add_u64 v[64:65], v[64:65], 0, s[30:31]
	s_cmpk_eq_i32 s5, 0x1fc0
	v_lshl_add_u64 v[66:67], v[66:67], 0, s[36:37]
	s_waitcnt lgkmcnt(0)
	s_barrier
	s_cbranch_scc1 .LBB0_1973

; DI void phase_gdn_seq(const Params& p, const Sub& s, char* lds_all) {
;     ...
;       bf16x8 Sb[4];
; #pragma unroll
;       for (int c = 0; c < 4; ++c) Sb[c] = mkfrag(S[2 * c], S[2 * c + 1]);
;       const float* Lt = (const float*)(lds_all + 131072 + ((rb < 128) ? (n & 1) : hh) * 1024);
;       bf16x8 VN[2], VD[2];
;       float eg[4][4];
; #pragma unroll
;       for (int c = 0; c < 2; ++c) { VN[c] = Sb[0]; VD[c] = Sb[0]; }
; #pragma unroll
;       for (int i = 0; i < 4; ++i)
; #pragma unroll
;         for (int j = 0; j < 4; ++j) eg[i][j] = 0.f;
;       if (act) {
;         f32x4 vn[4], vd[4], wsv[4];
;         bf16x8 aw[4][4];
;         float uu[4][4], gtv[4][4];
; #pragma unroll
;         for (int i = 0; i < 4; ++i)
; #pragma unroll
;           for (int c = 0; c < 4; ++c) aw[i][c] = ldfrag(Lw, 256, i * 16 + fr, 4 * c + fq);
; #pragma unroll
;         for (int i = 0; i < 4; ++i) {
;           const uint2 u2 = *(const uint2*)(Lu + ((wave * 4 + i) * 64 + lane) * 8);
;           uu[i][0] = __uint_as_float(u2.x << 16); uu[i][1] = __uint_as_float(u2.x & 0xffff0000u);
;           uu[i][2] = __uint_as_float(u2.y << 16); uu[i][3] = __uint_as_float(u2.y & 0xffff0000u);
;           { const float4 e4 = *(const float4*)(Lt + 64 + i * 16 + 4 * fq), g4 = *(const float4*)(Lt + i * 16 + 4 * fq);
;             gtv[i][0] = e4.x; gtv[i][1] = e4.y; gtv[i][2] = e4.z; gtv[i][3] = e4.w;
;             eg[i][0] = g4.x; eg[i][1] = g4.y; eg[i][2] = g4.z; eg[i][3] = g4.w; }
;         }
; #pragma unroll
;         for (int i = 0; i < 4; ++i) wsv[i] = (f32x4){0.f, 0.f, 0.f, 0.f};
; #pragma unroll
;         for (int c = 0; c < 4; ++c)
; #pragma unroll
;           for (int i = 0; i < 4; ++i) wsv[i] = MFMA16(aw[i][c], Sb[c], wsv[i]);
; #pragma unroll
;         for (int i = 0; i < 4; ++i) {
;           const f32x4 ws_ = wsv[i];
; #pragma unroll
;           for (int j = 0; j < 4; ++j) {
;             const float u = uu[i][j];
;             vn[i][j] = u - ws_[j];
;             vd[i][j] = vn[i][j] * gtv[i][j];
;           }
;         }
; #pragma unroll
;         for (int c = 0; c < 2; ++c) { VN[c] = mkfrag(vn[2 * c], vn[2 * c + 1]); VD[c] = mkfrag(vd[2 * c], vd[2 * c + 1]); }
;       }
;       if (act) {
; #pragma unroll
;       for (int ih = 0; ih < 2; ++ih) {
;         bf16x8 aq[2][4], aqk[2][2];
;         f32x4 qsv[2];
; #pragma unroll
;         for (int ii = 0; ii < 2; ++ii) {
.LBB0_1971:
	s_or_b64 exec, exec, s[0:1]
	s_cmp_eq_u64 s[6:7], 0
	s_cbranch_scc1 .Lseq_pf_skip
	v_bfe_u32 v240, v182, 6, 2
	s_lshl_b32 s68, s38, 7
	s_add_i32 s68, s68, s39
	s_add_i32 s68, s68, 3
	v_readfirstlane_b32 s72, v240
	s_lshl_b32 s69, s68, 3
	s_add_i32 s69, s69, s12
	s_lshr_b32 s70, s12, 1
	s_lshl_b32 s71, s68, 2
	s_add_i32 s71, s71, s70
	s_lshl_b32 s73, s69, 14
	s_lshl_b32 s74, s71, 14
	s_add_u32 s75, s73, 0x21a00000
	s_add_u32 s76, s74, 0x35f00000
	s_add_u32 s77, s74, 0x3a000000
	s_lshl_b32 s78, s100, 13
	s_add_u32 s78, s78, s73
	s_add_u32 s78, s78, 0x29c00000
	s_lshl_b32 s79, s69, 13
	s_add_u32 s79, s79, 0x31e00000
	s_cmp_eq_u32 s72, 1
	s_cselect_b32 s80, s76, s75
	s_cmp_eq_u32 s72, 2
	s_cselect_b32 s80, s77, s80
	s_add_u32 s81, s80, 0x2000
	s_cmp_eq_u32 s72, 3
	s_cselect_b32 s80, s78, s80
	s_cselect_b32 s81, s79, s81
	s_add_u32 s82, s10, s80
	s_addc_u32 s83, s11, 0
	s_add_u32 s84, s10, s81
	s_addc_u32 s85, s11, 0
	v_lshlrev_b32_e32 v241, 7, v46
	global_load_dword v242, v241, s[82:83]
	global_load_dword v243, v241, s[84:85]
.Lseq_pf_skip:
	s_and_saveexec_b64 s[0:1], vcc
	s_cbranch_execz .LBB0_1967
	v_lshrrev_b32_e32 v73, 4, v46
	v_bitop3_b32 v42, v73, v44, 7 bitop3:0x78
	v_lshl_add_u32 v47, v68, 8, s63
	v_lshlrev_b32_e32 v69, 4, v42
	v_add_u32_e32 v75, v47, v69
	s_waitcnt vmcnt(0)
	ds_read_b128 v[54:57], v75
	ds_read_b128 v[98:101], v75 offset:4096
	v_and_b32_e32 v48, 7, v44
	v_bitop3_b32 v44, v73, v48, 4 bitop3:0x36
	v_lshlrev_b32_e32 v77, 4, v44
	v_add_u32_e32 v79, v47, v77
	ds_read_b128 v[132:135], v79
	ds_read_b128 v[136:139], v79 offset:4096
	v_cvt_pk_bf16_f32 v50, v30, v31
	v_cvt_pk_bf16_f32 v51, v32, v33
	v_cvt_pk_bf16_f32 v52, v26, v27
	v_cvt_pk_bf16_f32 v53, v28, v29
	ds_read_b128 v[102:105], v75 offset:8192
	ds_read_b128 v[128:131], v75 offset:12288
	s_waitcnt lgkmcnt(0)
	v_mfma_f32_16x16x32_bf16 v[54:57], v[54:57], v[50:53], 0
	v_cvt_pk_bf16_f32 v42, v22, v23
	v_cvt_pk_bf16_f32 v43, v24, v25
	v_cvt_pk_bf16_f32 v44, v18, v19
	v_cvt_pk_bf16_f32 v45, v20, v21
	ds_read_b128 v[140:143], v79 offset:8192
	v_mfma_f32_16x16x32_bf16 v[98:101], v[98:101], v[50:53], 0
	v_bitop3_b32 v49, v73, v48, 8 bitop3:0x36
	v_lshl_add_u32 v81, v49, 4, v47
	v_bitop3_b32 v48, v73, v48, 12 bitop3:0x36
	v_mfma_f32_16x16x32_bf16 v[54:57], v[132:135], v[42:45], v[54:57]
	ds_read_b128 v[132:135], v79 offset:12288
	v_lshl_add_u32 v83, v48, 4, v47
	v_lshrrev_b32_e32 v0, 6, v34
	v_mfma_f32_16x16x32_bf16 v[102:105], v[102:105], v[50:53], 0
	s_lshl_b32 s8, s64, 10
	s_or_b32 s9, s8, 0x20000
	v_cvt_pk_bf16_f32 v38, v14, v15
	v_mfma_f32_16x16x32_bf16 v[128:131], v[128:131], v[50:53], 0
	v_cvt_pk_bf16_f32 v39, v16, v17
	v_cvt_pk_bf16_f32 v40, v10, v11
	v_cvt_pk_bf16_f32 v41, v12, v13
	v_mfma_f32_16x16x32_bf16 v[98:101], v[136:139], v[42:45], v[98:101]
	ds_read_b128 v[136:139], v81
	ds_read_b128 v[150:153], v81 offset:4096
	ds_read_b128 v[154:157], v83
	ds_read_b128 v[158:161], v83 offset:4096
	v_lshlrev_b32_e32 v47, 11, v0
	v_lshlrev_b32_e32 v48, 3, v46
	s_waitcnt lgkmcnt(5)
	v_mfma_f32_16x16x32_bf16 v[102:105], v[140:143], v[42:45], v[102:105]
	ds_read_b128 v[140:143], v81 offset:8192
	ds_read_b128 v[162:165], v81 offset:12288
	v_add3_u32 v85, s63, v47, v48
	v_and_or_b32 v87, v46, 48, s9
	s_waitcnt lgkmcnt(6)
	v_mfma_f32_16x16x32_bf16 v[128:131], v[132:135], v[42:45], v[128:131]
	ds_read2st64_b64 v[132:135], v85 offset0:112 offset1:113
	v_cvt_pk_bf16_f32 v34, v6, v7
	v_cvt_pk_bf16_f32 v35, v8, v9
	s_waitcnt lgkmcnt(6)
	v_mfma_f32_16x16x32_bf16 v[54:57], v[136:139], v[38:41], v[54:57]
	v_cvt_pk_bf16_f32 v36, v2, v3
	v_cvt_pk_bf16_f32 v37, v4, v5
	ds_read_b128 v[136:139], v83 offset:8192
	ds_read_b128 v[166:169], v83 offset:12288
	s_waitcnt lgkmcnt(7)
	v_mfma_f32_16x16x32_bf16 v[46:49], v[150:153], v[38:41], v[98:101]
	s_waitcnt lgkmcnt(2)
	v_lshlrev_b32_e32 v144, 16, v132
	v_and_b32_e32 v145, 0xffff0000, v132
	v_lshlrev_b32_e32 v150, 16, v135
	ds_read2st64_b64 v[98:101], v85 offset0:114 offset1:115
	v_mfma_f32_16x16x32_bf16 v[102:105], v[140:143], v[38:41], v[102:105]
	v_lshlrev_b32_e32 v140, 16, v133
	v_and_b32_e32 v141, 0xffff0000, v133
	v_lshlrev_b32_e32 v142, 16, v134
	v_mfma_f32_16x16x32_bf16 v[128:131], v[162:165], v[38:41], v[128:131]
	v_and_b32_e32 v143, 0xffff0000, v134
	v_and_b32_e32 v151, 0xffff0000, v135
	s_waitcnt lgkmcnt(0)
	v_lshlrev_b32_e32 v152, 16, v98
	v_mfma_f32_16x16x32_bf16 v[54:57], v[154:157], v[34:37], v[54:57]
	v_and_b32_e32 v153, 0xffff0000, v98
	v_lshlrev_b32_e32 v154, 16, v99
	v_and_b32_e32 v155, 0xffff0000, v99
	v_mfma_f32_16x16x32_bf16 v[46:49], v[158:161], v[34:37], v[46:49]
	v_lshlrev_b32_e32 v156, 16, v100
	v_and_b32_e32 v157, 0xffff0000, v100
	ds_read_b128 v[132:135], v87 offset:256
	v_mfma_f32_16x16x32_bf16 v[102:105], v[136:139], v[34:37], v[102:105]
	v_lshlrev_b32_e32 v136, 16, v101
	v_and_b32_e32 v137, 0xffff0000, v101
	v_pk_add_f32 v[138:139], v[144:145], v[54:55] neg_lo:[0,1] neg_hi:[0,1]
	v_mfma_f32_16x16x32_bf16 v[98:101], v[166:169], v[34:37], v[128:131]
	v_add_f32_e64 v140, v140, -v56
	v_add_f32_e64 v141, v141, -v57
	v_pk_add_f32 v[142:143], v[142:143], v[46:47] neg_lo:[0,1] neg_hi:[0,1]
	ds_read_b128 v[54:57], v87 offset:384
	ds_read_b128 v[128:131], v87 offset:320
	v_pk_add_f32 v[150:151], v[150:151], v[48:49] neg_lo:[0,1] neg_hi:[0,1]
	ds_read_b128 v[46:49], v87 offset:448
	v_pk_add_f32 v[104:105], v[154:155], v[104:105] neg_lo:[0,1] neg_hi:[0,1]
	v_pk_add_f32 v[98:99], v[156:157], v[98:99] neg_lo:[0,1] neg_hi:[0,1]
	v_pk_add_f32 v[154:155], v[136:137], v[100:101] neg_lo:[0,1] neg_hi:[0,1]
	s_waitcnt lgkmcnt(1)
	v_pk_mul_f32 v[144:145], v[128:129], v[142:143]
	v_pk_mul_f32 v[158:159], v[130:131], v[150:151]
	s_waitcnt lgkmcnt(0)
; #define MFMA16(a, b, c) __builtin_amdgcn_mfma_f32_16x16x32_bf16((a), (b), (c), 0, 0, 0)
; DI void phase_gdn_seq(const Params& p, const Sub& s, char* lds_all) {
;     ...
;       if (act) {
; #pragma unroll
;       for (int ih = 0; ih < 2; ++ih) {
;         bf16x8 aq[2][4], aqk[2][2];
;         f32x4 qsv[2];
; #pragma unroll
;         for (int ii = 0; ii < 2; ++ii) {
;           const int i = ih * 2 + ii;
; #pragma unroll
;           for (int c = 0; c < 4; ++c) aq[ii][c] = ldfrag(Lq, 256, i * 16 + fr, 4 * c + fq);
; #pragma unroll
;           for (int c = 0; c < 2; ++c) aqk[ii][c] = ldfrag(Lqk, 128, i * 16 + fr, 4 * c + fq);
;           qsv[ii] = (f32x4){0.f, 0.f, 0.f, 0.f};
;         }
; #pragma unroll
;         for (int c = 0; c < 4; ++c)
; #pragma unroll
;           for (int ii = 0; ii < 2; ++ii) qsv[ii] = MFMA16(aq[ii][c], Sb[c], qsv[ii]);
; #pragma unroll
;         for (int ii = 0; ii < 2; ++ii)
; #pragma unroll
;           for (int j = 0; j < 4; ++j) qsv[ii][j] *= eg[ih * 2 + ii][j];
; #pragma unroll
;         for (int c = 0; c < 2; ++c)
; #pragma unroll
;           for (int ii = 0; ii < 2; ++ii) qsv[ii] = MFMA16(aqk[ii][c], VN[c], qsv[ii]);
; #pragma unroll
;         for (int ii = 0; ii < 2; ++ii)
; #pragma unroll
;           for (int j = 0; j < 4; ++j) {
;             const int t = (ih * 2 + ii) * 16 + 4 * fq + j;
;             if (t < tv) O[(size_t)(row0 + t) * D + hv * 128 + dv0 + fr] = f2bf(qsv[ii][j]);
;           }
;       }
	v_pk_mul_f32 v[164:165], v[46:47], v[98:99]
	v_pk_mul_f32 v[166:167], v[48:49], v[154:155]
	ds_read_b128 v[46:49], v75 offset:16384
	ds_read_b128 v[128:131], v75 offset:20480
	v_pk_mul_f32 v[132:133], v[132:133], v[138:139]
	v_pk_mul_f32 v[134:135], v[134:135], v[140:141]
	v_pk_add_f32 v[152:153], v[152:153], v[102:103] neg_lo:[0,1] neg_hi:[0,1]
	v_cvt_pk_bf16_f32 v100, v138, v139
	v_pk_mul_f32 v[160:161], v[54:55], v[152:153]
	v_cvt_pk_bf16_f32 v54, v132, v133
	v_cvt_pk_bf16_f32 v55, v134, v135
	ds_read_b128 v[132:135], v79 offset:16384
	ds_read_b128 v[136:139], v79 offset:20480
	v_cvt_pk_bf16_f32 v101, v140, v141
	v_cvt_pk_bf16_f32 v102, v142, v143
	v_cvt_pk_bf16_f32 v103, v150, v151
	s_waitcnt lgkmcnt(2)
	v_mfma_f32_16x16x32_bf16 v[128:131], v[128:131], v[50:53], 0
	v_cvt_pk_bf16_f32 v140, v152, v153
	ds_read_b128 v[150:153], v81 offset:16384
	v_cvt_pk_bf16_f32 v143, v154, v155
	ds_read_b128 v[154:157], v81 offset:20480
	v_mfma_f32_16x16x32_bf16 v[46:49], v[46:49], v[50:53], 0
	v_mul_f32_e64 v162, v56, v104
	v_mul_f32_e64 v163, v57, v105
	v_cvt_pk_bf16_f32 v57, v158, v159
	s_lshl_b32 s9, s2, 1
	s_waitcnt lgkmcnt(2)
	v_mfma_f32_16x16x32_bf16 v[128:131], v[136:139], v[42:45], v[128:131]
	ds_read_b128 v[136:139], v83 offset:16384
	v_cvt_pk_bf16_f32 v141, v104, v105
	v_cvt_pk_bf16_f32 v142, v98, v99
	v_mfma_f32_16x16x32_bf16 v[132:135], v[132:135], v[42:45], v[46:49]
	v_lshl_or_b32 v0, v0, 5, s9
	v_lshl_add_u64 v[98:99], s[40:41], 0, v[0:1]
	v_lshlrev_b32_e32 v0, 1, v68
	v_lshl_add_u32 v49, v68, 7, s63
	v_add_u32_e32 v85, v49, v69
	s_waitcnt lgkmcnt(2)
	v_mfma_f32_16x16x32_bf16 v[132:135], v[150:153], v[38:41], v[132:135]
	ds_read_b128 v[150:153], v83 offset:20480
	v_cvt_pk_bf16_f32 v46, v160, v161
	v_cvt_pk_bf16_f32 v47, v162, v163
	s_waitcnt lgkmcnt(2)
	v_mfma_f32_16x16x32_bf16 v[128:131], v[154:157], v[38:41], v[128:131]
	ds_read_b128 v[154:157], v85 offset:49152
	v_cvt_pk_bf16_f32 v48, v164, v165
	v_add_u32_e32 v77, v49, v77
	s_waitcnt lgkmcnt(2)
	v_mfma_f32_16x16x32_bf16 v[132:135], v[136:139], v[34:37], v[132:135]
	ds_read_b128 v[136:139], v87
	ds_read_b128 v[158:161], v77 offset:49152
	ds_read_b128 v[162:165], v85 offset:51200
	s_add_i32 s9, s3, s5
	v_lshl_add_u64 v[68:69], v[98:99], 0, v[0:1]
	s_waitcnt lgkmcnt(2)
	s_nop 1
	v_pk_mul_f32 v[134:135], v[138:139], v[134:135]
	v_pk_mul_f32 v[132:133], v[136:137], v[132:133]
	v_lshl_add_u32 v98, v73, 2, s9
	v_ashrrev_i32_e32 v99, 31, v98
	v_mfma_f32_16x16x32_bf16 v[132:135], v[154:157], v[100:103], v[132:135]
	v_lshlrev_b64 v[104:105], 11, v[98:99]
	ds_read_b128 v[136:139], v77 offset:51200
	v_lshl_add_u64 v[104:105], v[68:69], 0, v[104:105]
	s_waitcnt lgkmcnt(2)
	v_mfma_f32_16x16x32_bf16 v[132:135], v[158:161], v[140:143], v[132:135]
	ds_read_b128 v[154:157], v79 offset:28672
	s_or_b32 s8, s8, 0x20200
	v_cvt_pk_bf16_f32 v56, v144, v145
	v_mfma_f32_16x16x32_bf16 v[128:131], v[150:153], v[34:37], v[128:131]
	ds_read_b128 v[150:153], v87 offset:64
	s_nop 2
	v_cvt_pk_bf16_f32 v0, v132, s0
	global_store_short v[104:105], v0, off
	v_add_u32_e32 v104, 1, v98
	v_ashrrev_i32_e32 v105, 31, v104
	v_lshlrev_b64 v[104:105], 11, v[104:105]
	s_waitcnt lgkmcnt(0)
	v_pk_mul_f32 v[130:131], v[152:153], v[130:131]
	v_pk_mul_f32 v[128:129], v[150:151], v[128:129]
	v_cvt_pk_bf16_f32 v0, v133, s0
	v_lshl_add_u64 v[104:105], v[68:69], 0, v[104:105]
	v_mfma_f32_16x16x32_bf16 v[128:131], v[162:165], v[100:103], v[128:131]
	global_store_short v[104:105], v0, off
	v_add_u32_e32 v104, 2, v98
	v_ashrrev_i32_e32 v105, 31, v104
	v_lshlrev_b64 v[104:105], 11, v[104:105]
	v_cvt_pk_bf16_f32 v0, v134, s0
	v_lshl_add_u64 v[104:105], v[68:69], 0, v[104:105]
	global_store_short v[104:105], v0, off
	v_cvt_pk_bf16_f32 v0, v135, s0
	ds_read_b128 v[132:135], v75 offset:24576
	ds_read_b128 v[150:153], v79 offset:24576
	v_mfma_f32_16x16x32_bf16 v[128:131], v[136:139], v[140:143], v[128:131]
	ds_read_b128 v[136:139], v75 offset:28672
	v_add_u32_e32 v104, 3, v98
	v_ashrrev_i32_e32 v105, 31, v104
	s_waitcnt lgkmcnt(2)
	v_mfma_f32_16x16x32_bf16 v[132:135], v[132:135], v[50:53], 0
	v_lshlrev_b64 v[104:105], 11, v[104:105]
	v_lshl_add_u64 v[104:105], v[68:69], 0, v[104:105]
	global_store_short v[104:105], v0, off
	s_waitcnt lgkmcnt(0)
	v_mfma_f32_16x16x32_bf16 v[50:53], v[136:139], v[50:53], 0
	ds_read_b128 v[136:139], v81 offset:24576
	v_add_u32_e32 v104, 16, v98
	v_ashrrev_i32_e32 v105, 31, v104
	v_mfma_f32_16x16x32_bf16 v[132:135], v[150:153], v[42:45], v[132:135]
	ds_read_b128 v[150:153], v81 offset:28672
	v_lshlrev_b64 v[104:105], 11, v[104:105]
	v_lshl_add_u64 v[104:105], v[68:69], 0, v[104:105]
	v_cvt_pk_bf16_f32 v0, v128, s0
	v_mfma_f32_16x16x32_bf16 v[42:45], v[154:157], v[42:45], v[50:53]
	global_store_short v[104:105], v0, off
	v_add_u32_e32 v104, 17, v98
	v_ashrrev_i32_e32 v105, 31, v104
	ds_read_b128 v[50:53], v83 offset:24576
	s_waitcnt lgkmcnt(2)
	v_mfma_f32_16x16x32_bf16 v[132:135], v[136:139], v[38:41], v[132:135]
	ds_read_b128 v[136:139], v83 offset:28672
	v_lshlrev_b64 v[104:105], 11, v[104:105]
	v_lshl_add_u64 v[104:105], v[68:69], 0, v[104:105]
	v_cvt_pk_bf16_f32 v0, v129, s0
	global_store_short v[104:105], v0, off
	v_add_u32_e32 v104, 18, v98
	s_waitcnt lgkmcnt(2)
	v_mfma_f32_16x16x32_bf16 v[38:41], v[150:153], v[38:41], v[42:45]
	v_ashrrev_i32_e32 v105, 31, v104
	v_lshlrev_b64 v[104:105], 11, v[104:105]
	v_lshl_add_u64 v[104:105], v[68:69], 0, v[104:105]
	ds_read_b128 v[42:45], v85 offset:53248
	v_cvt_pk_bf16_f32 v0, v130, s0
	global_store_short v[104:105], v0, off
	s_waitcnt lgkmcnt(2)
; #define MFMA16(a, b, c) __builtin_amdgcn_mfma_f32_16x16x32_bf16((a), (b), (c), 0, 0, 0)
; DI void phase_gdn_seq(const Params& p, const Sub& s, char* lds_all) {
;     ...
; #pragma unroll
;         for (int ii = 0; ii < 2; ++ii)
; #pragma unroll
;           for (int j = 0; j < 4; ++j) {
;             const int t = (ih * 2 + ii) * 16 + 4 * fq + j;
;             if (t < tv) O[(size_t)(row0 + t) * D + hv * 128 + dv0 + fr] = f2bf(qsv[ii][j]);
;           }
;       }
;       const float dec = Lt[128];
;       {
;         bf16x8 ak[8][2];
; #pragma unroll
;         for (int m = 0; m < 8; ++m) {
; #pragma unroll
;           for (int c = 0; c < 2; ++c) ak[m][c] = ldfrag(Lk, 128, m * 16 + fr, 4 * c + fq);
;           S[m] = S[m] * dec;
;         }
; #pragma unroll
;         for (int c = 0; c < 2; ++c)
; #pragma unroll
;           for (int m = 0; m < 8; ++m) S[m] = MFMA16(ak[m][c], VD[c], S[m]);
	v_mfma_f32_16x16x32_bf16 v[50:53], v[50:53], v[34:37], v[132:135]
	s_nop 2
	ds_read_b128 v[132:135], v87 offset:128
	ds_read_b128 v[150:153], v77 offset:53248
	ds_read_b128 v[154:157], v85 offset:55296
	v_cvt_pk_bf16_f32 v0, v131, s0
	v_cvt_pk_bf16_f32 v49, v166, v167
	s_waitcnt lgkmcnt(4)
	v_mfma_f32_16x16x32_bf16 v[34:37], v[136:139], v[34:37], v[38:41]
	s_waitcnt lgkmcnt(2)
	v_pk_mul_f32 v[52:53], v[134:135], v[52:53]
	v_pk_mul_f32 v[50:51], v[132:133], v[50:51]
	ds_read_b128 v[38:41], v87 offset:192
	s_nop 0
	v_mfma_f32_16x16x32_bf16 v[42:45], v[42:45], v[100:103], v[50:53]
	s_nop 2
	ds_read_b128 v[50:53], v77 offset:55296
	s_waitcnt lgkmcnt(1)
	v_pk_mul_f32 v[34:35], v[38:39], v[34:35]
	v_add_u32_e32 v38, 19, v98
	v_pk_mul_f32 v[36:37], v[40:41], v[36:37]
	v_ashrrev_i32_e32 v39, 31, v38
	s_nop 0
	v_mfma_f32_16x16x32_bf16 v[34:37], v[154:157], v[100:103], v[34:37]
	v_lshlrev_b64 v[100:101], 11, v[38:39]
	v_mfma_f32_16x16x32_bf16 v[38:41], v[150:153], v[140:143], v[42:45]
	s_nop 2
	v_lshl_add_u64 v[42:43], v[68:69], 0, v[100:101]
	global_store_short v[42:43], v0, off
	v_add_u32_e32 v42, 32, v98
	v_ashrrev_i32_e32 v43, 31, v42
	v_lshlrev_b64 v[42:43], 11, v[42:43]
	v_lshl_add_u64 v[42:43], v[68:69], 0, v[42:43]
	v_cvt_pk_bf16_f32 v0, v38, s0
	global_store_short v[42:43], v0, off
	v_add_u32_e32 v42, 33, v98
	v_ashrrev_i32_e32 v43, 31, v42
	v_add_u32_e32 v38, 34, v98
	v_lshlrev_b64 v[42:43], 11, v[42:43]
	v_cvt_pk_bf16_f32 v0, v39, s0
	v_ashrrev_i32_e32 v39, 31, v38
	v_lshl_add_u64 v[42:43], v[68:69], 0, v[42:43]
	v_lshlrev_b64 v[38:39], 11, v[38:39]
	global_store_short v[42:43], v0, off
	v_lshl_add_u64 v[38:39], v[68:69], 0, v[38:39]
	v_cvt_pk_bf16_f32 v0, v40, s0
	global_store_short v[38:39], v0, off
	v_add_u32_e32 v38, 35, v98
	v_ashrrev_i32_e32 v39, 31, v38
	v_lshlrev_b64 v[38:39], 11, v[38:39]
	v_lshl_add_u64 v[38:39], v[68:69], 0, v[38:39]
	v_cvt_pk_bf16_f32 v0, v41, s0
	global_store_short v[38:39], v0, off
	v_add_u32_e32 v38, 48, v98
	v_ashrrev_i32_e32 v39, 31, v38
	v_mov_b32_e32 v0, s8
	s_waitcnt lgkmcnt(0)
	v_mfma_f32_16x16x32_bf16 v[34:37], v[50:53], v[140:143], v[34:37]
	v_lshlrev_b64 v[42:43], 11, v[38:39]
	ds_read_b128 v[38:41], v85 offset:32768
	ds_read_b32 v0, v0
	v_lshl_add_u64 v[50:51], v[68:69], 0, v[42:43]
	ds_read_b128 v[42:45], v85 offset:34816
	s_nop 2
	v_cvt_pk_bf16_f32 v34, v34, s0
	global_store_short v[50:51], v34, off
	s_waitcnt lgkmcnt(1)
	v_pk_mul_f32 v[32:33], v[32:33], v[0:1] op_sel_hi:[1,0]
	v_pk_mul_f32 v[30:31], v[30:31], v[0:1] op_sel_hi:[1,0]
	ds_read_b128 v[50:53], v85 offset:36864
	v_pk_mul_f32 v[28:29], v[28:29], v[0:1] op_sel_hi:[1,0]
	v_mfma_f32_16x16x32_bf16 v[30:33], v[38:41], v[54:57], v[30:33]
	ds_read_b128 v[38:41], v85 offset:38912
	v_pk_mul_f32 v[26:27], v[26:27], v[0:1] op_sel_hi:[1,0]
	v_pk_mul_f32 v[24:25], v[24:25], v[0:1] op_sel_hi:[1,0]
	v_pk_mul_f32 v[22:23], v[22:23], v[0:1] op_sel_hi:[1,0]
	s_waitcnt lgkmcnt(2)
	v_mfma_f32_16x16x32_bf16 v[26:29], v[42:45], v[54:57], v[26:29]
	ds_read_b128 v[42:45], v85 offset:40960
	v_pk_mul_f32 v[20:21], v[20:21], v[0:1] op_sel_hi:[1,0]
	v_pk_mul_f32 v[18:19], v[18:19], v[0:1] op_sel_hi:[1,0]
	s_waitcnt lgkmcnt(2)
	v_mfma_f32_16x16x32_bf16 v[22:25], v[50:53], v[54:57], v[22:25]
	ds_read_b128 v[50:53], v85 offset:43008
	v_pk_mul_f32 v[16:17], v[16:17], v[0:1] op_sel_hi:[1,0]
	v_pk_mul_f32 v[14:15], v[14:15], v[0:1] op_sel_hi:[1,0]
	s_waitcnt lgkmcnt(2)
	v_mfma_f32_16x16x32_bf16 v[18:21], v[38:41], v[54:57], v[18:21]
	ds_read_b128 v[38:41], v85 offset:45056
	v_pk_mul_f32 v[12:13], v[12:13], v[0:1] op_sel_hi:[1,0]
	v_pk_mul_f32 v[10:11], v[10:11], v[0:1] op_sel_hi:[1,0]
	s_waitcnt lgkmcnt(2)
	v_mfma_f32_16x16x32_bf16 v[14:17], v[42:45], v[54:57], v[14:17]
	ds_read_b128 v[42:45], v85 offset:47104
	v_pk_mul_f32 v[8:9], v[8:9], v[0:1] op_sel_hi:[1,0]
	v_pk_mul_f32 v[6:7], v[6:7], v[0:1] op_sel_hi:[1,0]
	s_waitcnt lgkmcnt(2)
	v_mfma_f32_16x16x32_bf16 v[10:13], v[50:53], v[54:57], v[10:13]
	ds_read_b128 v[50:53], v77 offset:32768
	v_pk_mul_f32 v[4:5], v[4:5], v[0:1] op_sel_hi:[1,0]
	v_pk_mul_f32 v[2:3], v[2:3], v[0:1] op_sel_hi:[1,0]
	s_waitcnt lgkmcnt(2)
	v_mfma_f32_16x16x32_bf16 v[6:9], v[38:41], v[54:57], v[6:9]
	ds_read_b128 v[38:41], v77 offset:34816
	v_add_u32_e32 v34, 50, v98
	v_cvt_pk_bf16_f32 v0, v35, s0
	s_waitcnt lgkmcnt(2)
	v_mfma_f32_16x16x32_bf16 v[2:5], v[42:45], v[54:57], v[2:5]
	v_add_u32_e32 v54, 49, v98
	v_ashrrev_i32_e32 v55, 31, v54
	ds_read_b128 v[42:45], v77 offset:36864
	s_waitcnt lgkmcnt(2)
	v_mfma_f32_16x16x32_bf16 v[30:33], v[50:53], v[46:49], v[30:33]
	v_lshlrev_b64 v[50:51], 11, v[54:55]
	v_lshl_add_u64 v[54:55], v[68:69], 0, v[50:51]
	ds_read_b128 v[50:53], v77 offset:38912
	s_waitcnt lgkmcnt(2)
	v_mfma_f32_16x16x32_bf16 v[26:29], v[38:41], v[46:49], v[26:29]
	ds_read_b128 v[38:41], v77 offset:40960
	v_ashrrev_i32_e32 v35, 31, v34
	v_lshlrev_b64 v[34:35], 11, v[34:35]
	s_waitcnt lgkmcnt(2)
	v_mfma_f32_16x16x32_bf16 v[22:25], v[42:45], v[46:49], v[22:25]
	ds_read_b128 v[42:45], v77 offset:43008
	global_store_short v[54:55], v0, off
	v_lshl_add_u64 v[34:35], v[68:69], 0, v[34:35]
	s_waitcnt lgkmcnt(2)
	v_mfma_f32_16x16x32_bf16 v[18:21], v[50:53], v[46:49], v[18:21]
	ds_read_b128 v[50:53], v77 offset:45056
	v_cvt_pk_bf16_f32 v0, v36, s0
	global_store_short v[34:35], v0, off
	s_waitcnt lgkmcnt(2)
	v_mfma_f32_16x16x32_bf16 v[14:17], v[38:41], v[46:49], v[14:17]
	ds_read_b128 v[38:41], v77 offset:47104
	v_add_u32_e32 v34, 51, v98
	v_ashrrev_i32_e32 v35, 31, v34
	s_waitcnt lgkmcnt(2)
	v_mfma_f32_16x16x32_bf16 v[10:13], v[42:45], v[46:49], v[10:13]
	v_lshlrev_b64 v[34:35], 11, v[34:35]
	v_lshl_add_u64 v[34:35], v[68:69], 0, v[34:35]
	v_cvt_pk_bf16_f32 v0, v37, s0
	s_waitcnt lgkmcnt(1)
	v_mfma_f32_16x16x32_bf16 v[6:9], v[50:53], v[46:49], v[6:9]
	global_store_short v[34:35], v0, off
	s_waitcnt lgkmcnt(0)
	v_mfma_f32_16x16x32_bf16 v[2:5], v[38:41], v[46:49], v[2:5]
	s_branch .LBB0_1967
